# attention: s_setprio 1 around the MFMA segment of each tile step
# speedup vs baseline: 1.0171x; 1.0170x over previous
.LBB0_1049:
	s_waitcnt lgkmcnt(0)
	s_barrier
	s_setprio 1
	s_and_b64 vcc, exec, s[4:5]
	s_cbranch_vccnz .LBB0_1051
	v_add_u32_e32 v249, s60, v157
	ds_read_b128 v[236:239], v249
	ds_read_b128 v[240:243], v249 offset:6656
	ds_read_b128 v[244:247], v249 offset:32
	v_mfma_f32_32x32x16_bf16 v[2:17], v[164:167], v[122:125], v[2:17]
	ds_read_b128 v[164:167], v249 offset:6688
	v_mfma_f32_32x32x16_bf16 v[18:33], v[168:171], v[122:125], v[18:33]
	ds_read_b128 v[168:171], v249 offset:64
	v_mfma_f32_32x32x16_bf16 v[2:17], v[172:175], v[126:129], v[2:17]
	ds_read_b128 v[172:175], v249 offset:6720
	v_mfma_f32_32x32x16_bf16 v[18:33], v[176:179], v[126:129], v[18:33]
	ds_read_b128 v[176:179], v249 offset:96
	v_mfma_f32_32x32x16_bf16 v[2:17], v[180:183], v[130:133], v[2:17]
	ds_read_b128 v[180:183], v249 offset:6752
	v_mfma_f32_32x32x16_bf16 v[18:33], v[220:223], v[130:133], v[18:33]
	ds_read_b128 v[220:223], v249 offset:128
	v_mfma_f32_32x32x16_bf16 v[2:17], v[224:227], v[134:137], v[2:17]
	ds_read_b128 v[224:227], v249 offset:6784
	v_mfma_f32_32x32x16_bf16 v[18:33], v[232:235], v[134:137], v[18:33]
	ds_read_b128 v[232:235], v249 offset:160

.LBB0_1053:
	s_setprio 0
	s_add_i32 s0, s57, 0
	v_add3_u32 v0, s0, v152, v153
	s_waitcnt vmcnt(4)
	ds_write_b128 v0, v[86:89]
	v_add3_u32 v0, s0, v154, v155
	s_waitcnt vmcnt(3)
	ds_write_b128 v0, v[90:93]
	v_add3_u32 v0, s0, v156, v140
	s_add_i32 s0, s59, 4
	s_cmp_lt_u32 s59, s48
	s_cselect_b32 s0, s0, s50
	s_lshl_b32 s8, s0, 6
	ds_write_b128 v0, v[82:85] offset:13312
	v_add_u32_e32 v0, s8, v150
	s_waitcnt lgkmcnt(0)
	s_barrier
	v_mad_i64_i32 v[82:83], s[0:1], v0, s3, v[144:145]
	v_add_u32_e32 v0, s8, v151
	v_mad_i64_i32 v[84:85], s[0:1], v0, s3, v[146:147]
	global_load_dwordx4 v[86:89], v[82:83], off
	global_load_dwordx4 v[90:93], v[84:85], off
	v_lshl_add_u64 v[82:83], s[8:9], 1, v[142:143]
	global_load_dwordx4 v[82:85], v[82:83], off
	v_add_u32_e32 v248, s60, v160
	ds_read_b128 v[164:167], v248 offset:13312
	ds_read_b128 v[168:171], v248 offset:17920
	ds_read_b128 v[172:175], v248 offset:13344
	ds_read_b128 v[176:179], v248 offset:17952
	ds_read_b128 v[180:183], v248 offset:13376
	ds_read_b128 v[220:223], v248 offset:17984
	ds_read_b128 v[224:227], v248 offset:13408
	ds_read_b128 v[232:235], v248 offset:18016
	s_add_i32 s62, s62, 1
	s_cmp_lt_i32 s62, 0
	s_cselect_b64 s[0:1], -1, 0
	s_add_i32 s4, s61, 64
	s_cmp_le_i32 s4, s51
	s_cselect_b64 s[4:5], -1, 0
	s_or_b64 s[0:1], s[0:1], s[4:5]
	v_cndmask_b32_e64 v0, 0, 1, s[0:1]
	v_cmp_ne_u32_e64 s[4:5], 1, v0
	s_andn2_b64 vcc, exec, s[0:1]
	s_cbranch_vccnz .LBB0_1059
	s_cmp_lt_i32 s62, 0
	s_cbranch_scc1 .LBB0_1056
	v_add_u32_e32 v0, s54, v161
	v_add_u32_e32 v107, 0x60, v0
	v_add_u32_e32 v106, 64, v0
	v_cmp_le_i32_e32 vcc, v107, v159
	s_nop 1
	v_cndmask_b32_e32 v50, v149, v50, vcc
	v_cmp_lt_i32_e32 vcc, v106, v159
	s_nop 1
	v_cndmask_b32_e32 v35, v149, v35, vcc
	v_cmp_le_i32_e32 vcc, v106, v159
	v_add_u32_e32 v106, 0x61, v0
	s_nop 0
	v_cndmask_b32_e32 v34, v149, v34, vcc
	v_cmp_le_i32_e32 vcc, v106, v159
	v_add_u32_e32 v106, 0x42, v0
	s_nop 0
	v_cndmask_b32_e32 v51, v149, v51, vcc
	v_cmp_le_i32_e32 vcc, v106, v159
	v_add_u32_e32 v106, 0x62, v0
	s_nop 0
	v_cndmask_b32_e32 v36, v149, v36, vcc
	v_cmp_le_i32_e32 vcc, v106, v159
	v_add_u32_e32 v106, 0x43, v0
	s_nop 0
	v_cndmask_b32_e32 v52, v149, v52, vcc
	v_cmp_le_i32_e32 vcc, v106, v159
	v_add_u32_e32 v106, 0x63, v0
	s_nop 0
	v_cndmask_b32_e32 v37, v149, v37, vcc
	v_cmp_le_i32_e32 vcc, v106, v159
	v_add_u32_e32 v106, 0x48, v0
	s_nop 0
	v_cndmask_b32_e32 v53, v149, v53, vcc
	v_cmp_le_i32_e32 vcc, v106, v159
	v_add_u32_e32 v106, 0x68, v0
	s_nop 0
	v_cndmask_b32_e32 v38, v149, v38, vcc
	v_cmp_le_i32_e32 vcc, v106, v159
	v_add_u32_e32 v106, 0x49, v0
	s_nop 0
	v_cndmask_b32_e32 v54, v149, v54, vcc
	v_cmp_le_i32_e32 vcc, v106, v159
	v_add_u32_e32 v106, 0x69, v0
	s_nop 0
	v_cndmask_b32_e32 v39, v149, v39, vcc
	v_cmp_le_i32_e32 vcc, v106, v159
	v_add_u32_e32 v106, 0x4a, v0
	s_nop 0
	v_cndmask_b32_e32 v55, v149, v55, vcc
	v_cmp_le_i32_e32 vcc, v106, v159
	v_add_u32_e32 v106, 0x6a, v0
	s_nop 0
	v_cndmask_b32_e32 v40, v149, v40, vcc
	v_cmp_le_i32_e32 vcc, v106, v159
	v_add_u32_e32 v106, 0x4b, v0
	s_nop 0
	v_cndmask_b32_e32 v56, v149, v56, vcc
	v_cmp_le_i32_e32 vcc, v106, v159
	v_add_u32_e32 v106, 0x6b, v0
	s_nop 0
	v_cndmask_b32_e32 v41, v149, v41, vcc
	v_cmp_le_i32_e32 vcc, v106, v159
	v_add_u32_e32 v106, 0x50, v0
	s_nop 0
	v_cndmask_b32_e32 v57, v149, v57, vcc
	v_cmp_le_i32_e32 vcc, v106, v159
	v_add_u32_e32 v106, 0x70, v0
	s_nop 0
	v_cndmask_b32_e32 v42, v149, v42, vcc
	v_cmp_le_i32_e32 vcc, v106, v159
	v_add_u32_e32 v106, 0x51, v0
	s_nop 0
	v_cndmask_b32_e32 v58, v149, v58, vcc
	v_cmp_le_i32_e32 vcc, v106, v159
	v_add_u32_e32 v106, 0x71, v0
	s_nop 0
	v_cndmask_b32_e32 v43, v149, v43, vcc
	v_cmp_le_i32_e32 vcc, v106, v159
	v_add_u32_e32 v106, 0x52, v0
	s_nop 0
	v_cndmask_b32_e32 v59, v149, v59, vcc
	v_cmp_le_i32_e32 vcc, v106, v159
	v_add_u32_e32 v106, 0x72, v0
	s_nop 0
	v_cndmask_b32_e32 v44, v149, v44, vcc
	v_cmp_le_i32_e32 vcc, v106, v159
	v_add_u32_e32 v106, 0x53, v0
	s_nop 0
	v_cndmask_b32_e32 v60, v149, v60, vcc
	v_cmp_le_i32_e32 vcc, v106, v159
	v_add_u32_e32 v106, 0x73, v0
	s_nop 0
	v_cndmask_b32_e32 v45, v149, v45, vcc
	v_cmp_le_i32_e32 vcc, v106, v159
	v_add_u32_e32 v106, 0x58, v0
	s_nop 0
	v_cndmask_b32_e32 v61, v149, v61, vcc
	v_cmp_le_i32_e32 vcc, v106, v159
	v_add_u32_e32 v106, 0x78, v0
	s_nop 0
	v_cndmask_b32_e32 v46, v149, v46, vcc
	v_cmp_le_i32_e32 vcc, v106, v159
	v_add_u32_e32 v106, 0x59, v0
	s_nop 0
	v_cndmask_b32_e32 v62, v149, v62, vcc
	v_cmp_le_i32_e32 vcc, v106, v159
	v_add_u32_e32 v106, 0x79, v0
	s_nop 0
	v_cndmask_b32_e32 v47, v149, v47, vcc
	v_cmp_le_i32_e32 vcc, v106, v159
	v_add_u32_e32 v106, 0x5a, v0
	s_nop 0
	v_cndmask_b32_e32 v63, v149, v63, vcc
	v_cmp_le_i32_e32 vcc, v106, v159
	v_add_u32_e32 v106, 0x7a, v0
	s_nop 0
	v_cndmask_b32_e32 v48, v149, v48, vcc
	v_cmp_le_i32_e32 vcc, v106, v159
	v_add_u32_e32 v106, 0x5b, v0
	v_add_u32_e32 v0, 0x7b, v0
	v_cndmask_b32_e32 v64, v149, v64, vcc
	v_cmp_le_i32_e32 vcc, v106, v159
	s_nop 1
	v_cndmask_b32_e32 v49, v149, v49, vcc
	v_cmp_le_i32_e32 vcc, v0, v159
	s_nop 1
	v_cndmask_b32_e32 v65, v149, v65, vcc

.LBB0_1059:
	s_waitcnt lgkmcnt(0)
	s_barrier
	s_setprio 1
	s_and_b64 vcc, exec, s[4:5]
	s_cbranch_vccnz .LBB0_1061
	v_add_u32_e32 v249, s57, v157
	ds_read_b128 v[236:239], v249
	ds_read_b128 v[240:243], v249 offset:6656
	ds_read_b128 v[244:247], v249 offset:32
	v_mfma_f32_32x32x16_bf16 v[2:17], v[164:167], v[106:109], v[2:17]
	ds_read_b128 v[164:167], v249 offset:6688
	v_mfma_f32_32x32x16_bf16 v[18:33], v[168:171], v[106:109], v[18:33]
	ds_read_b128 v[168:171], v249 offset:64
	v_mfma_f32_32x32x16_bf16 v[2:17], v[172:175], v[110:113], v[2:17]
	ds_read_b128 v[172:175], v249 offset:6720
	v_mfma_f32_32x32x16_bf16 v[18:33], v[176:179], v[110:113], v[18:33]
	ds_read_b128 v[176:179], v249 offset:96
	v_mfma_f32_32x32x16_bf16 v[2:17], v[180:183], v[114:117], v[2:17]
	ds_read_b128 v[180:183], v249 offset:6752
	v_mfma_f32_32x32x16_bf16 v[18:33], v[220:223], v[114:117], v[18:33]
	ds_read_b128 v[220:223], v249 offset:128
	v_mfma_f32_32x32x16_bf16 v[2:17], v[224:227], v[118:121], v[2:17]
	ds_read_b128 v[224:227], v249 offset:6784
	v_mfma_f32_32x32x16_bf16 v[18:33], v[232:235], v[118:121], v[18:33]
	ds_read_b128 v[232:235], v249 offset:160

; template <int DK, int DV>
; __device__ __forceinline__ void attn_unit(LAS unsigned char* lds, const bf16* Qp, int ldq, const bf16* Kp, int ldk, const bf16* VTp, bf16* Op, int ldo, int qb) {
;     ...
;     for (int t = 0; t < NT; t += 2) {
;         ATT_STEP(t, kra, vra, krb, vrb);
;         ATT_STEP(t + 1, krb, vrb, kra, vra);
;     }
.LBB0_1063:
	s_setprio 0
	s_add_i32 s0, s58, 0
	v_add3_u32 v0, s0, v152, v153
	s_waitcnt vmcnt(5)
	ds_write_b128 v0, v[98:101]
	v_add3_u32 v0, s0, v154, v155
	s_waitcnt vmcnt(4)
	ds_write_b128 v0, v[94:97]
	v_add3_u32 v0, s0, v156, v140
	s_waitcnt vmcnt(3)
	ds_write_b128 v0, v[102:105] offset:13312
	s_waitcnt lgkmcnt(0)
	s_barrier
	s_addk_i32 s54, 0x80
	s_and_b64 vcc, exec, s[4:5]
	s_cbranch_vccnz .LBB0_1065
	s_mov_b32 s0, s57
	s_mov_b32 s57, s60
	s_branch .LBB0_1037

.LBB0_1084:
	s_waitcnt lgkmcnt(0)
	s_barrier
	s_setprio 1
	s_and_b64 vcc, exec, s[4:5]
	s_cbranch_vccnz .LBB0_1086
	v_add_u32_e32 v0, s51, v190
	ds_read_b128 v[196:199], v0 offset:9216
	ds_read_b128 v[200:203], v0 offset:9248
	s_waitcnt lgkmcnt(1)
	v_mfma_f32_32x32x16_bf16 v[64:79], v[196:199], v[156:159], v[64:79]
	ds_read_b128 v[196:199], v0 offset:13824
	ds_read_b128 v[204:207], v0 offset:13856
	s_waitcnt lgkmcnt(1)
	v_mfma_f32_32x32x16_bf16 v[48:63], v[196:199], v[156:159], v[48:63]
	ds_read_b128 v[196:199], v0 offset:18432
	ds_read_b128 v[208:211], v0 offset:18464
	s_waitcnt lgkmcnt(1)
	v_mfma_f32_32x32x16_bf16 v[32:47], v[196:199], v[156:159], v[32:47]
	ds_read_b128 v[196:199], v0 offset:23040
	ds_read_b128 v[212:215], v0 offset:23072
	v_mfma_f32_32x32x16_bf16 v[64:79], v[200:203], v[160:163], v[64:79]
	s_waitcnt lgkmcnt(1)
	v_mfma_f32_32x32x16_bf16 v[16:31], v[196:199], v[156:159], v[16:31]
	ds_read_b128 v[196:199], v0 offset:9280
	ds_read_b128 v[200:203], v0 offset:9312
	v_mfma_f32_32x32x16_bf16 v[48:63], v[204:207], v[160:163], v[48:63]
	v_mfma_f32_32x32x16_bf16 v[32:47], v[208:211], v[160:163], v[32:47]
	s_waitcnt lgkmcnt(1)
	v_mfma_f32_32x32x16_bf16 v[64:79], v[196:199], v[164:167], v[64:79]
	ds_read_b128 v[196:199], v0 offset:13888
	ds_read_b128 v[204:207], v0 offset:13920
	v_mfma_f32_32x32x16_bf16 v[16:31], v[212:215], v[160:163], v[16:31]
	s_waitcnt lgkmcnt(1)
	v_mfma_f32_32x32x16_bf16 v[48:63], v[196:199], v[164:167], v[48:63]
	ds_read_b128 v[196:199], v0 offset:18496
	ds_read_b128 v[208:211], v0 offset:18528
	s_waitcnt lgkmcnt(1)
	v_mfma_f32_32x32x16_bf16 v[32:47], v[196:199], v[164:167], v[32:47]
	ds_read_b128 v[196:199], v0 offset:23104
	ds_read_b128 v[212:215], v0 offset:23136
	s_waitcnt lgkmcnt(1)
	v_mfma_f32_32x32x16_bf16 v[16:31], v[196:199], v[164:167], v[16:31]
	v_mfma_f32_32x32x16_bf16 v[64:79], v[200:203], v[168:171], v[64:79]
	v_mfma_f32_32x32x16_bf16 v[48:63], v[204:207], v[168:171], v[48:63]
	v_mfma_f32_32x32x16_bf16 v[32:47], v[208:211], v[168:171], v[32:47]
	s_waitcnt lgkmcnt(0)
	v_mfma_f32_32x32x16_bf16 v[16:31], v[212:215], v[168:171], v[16:31]

.LBB0_1088:
	s_setprio 0
	s_add_i32 s0, s54, 4
	v_add_u32_e32 v14, s50, v188
	s_cmp_lt_u32 s54, s43
	s_waitcnt vmcnt(3)
	ds_write_b128 v14, v[136:139]
	v_add_u32_e32 v14, s50, v186
	s_cselect_b32 s0, s0, s45
	v_add_u32_e32 v15, v14, v175
	v_add_u32_e32 v14, v14, v187
	s_lshl_b32 s8, s0, 6
	ds_write_b128 v15, v[128:131] offset:9216
	ds_write_b128 v14, v[132:135] offset:9216
	v_add_u32_e32 v14, s8, v174
	v_ashrrev_i32_e32 v15, 31, v14
	v_lshlrev_b64 v[14:15], 10, v[14:15]
	v_lshl_add_u64 v[132:133], s[8:9], 1, v[176:177]
	s_waitcnt lgkmcnt(0)
	s_barrier
	v_lshl_add_u64 v[14:15], v[182:183], 0, v[14:15]
	v_lshl_add_u64 v[128:129], v[132:133], 0, v[178:179]
	global_load_dwordx4 v[136:139], v[14:15], off
	s_nop 0
	global_load_dwordx4 v[128:131], v[128:129], off
	v_lshl_add_u64 v[14:15], v[132:133], 0, v[180:181]
	global_load_dwordx4 v[132:135], v[14:15], off
	s_add_i32 s57, s57, 1
	s_cmp_lt_i32 s57, 0
	s_cselect_b64 s[0:1], -1, 0
	s_add_i32 s4, s56, 64
	s_cmp_le_i32 s4, s46
	s_cselect_b64 s[4:5], -1, 0
	s_or_b64 s[0:1], s[0:1], s[4:5]
	v_cndmask_b32_e64 v14, 0, 1, s[0:1]
	v_cmp_ne_u32_e64 s[4:5], 1, v14
	s_andn2_b64 vcc, exec, s[0:1]
	s_cbranch_vccnz .LBB0_1094
	s_cmp_lt_i32 s57, 0
	s_cbranch_scc1 .LBB0_1091
	v_add_u32_e32 v14, s47, v194
	v_add_u32_e32 v140, 0x60, v14
	v_add_u32_e32 v15, 64, v14
	v_cmp_le_i32_e32 vcc, v140, v192
	s_nop 1
	v_cndmask_b32_e32 v96, v185, v96, vcc
	v_cmp_lt_i32_e32 vcc, v15, v192
	s_nop 1
	v_cndmask_b32_e32 v81, v185, v81, vcc
	v_cmp_le_i32_e32 vcc, v15, v192
	v_add_u32_e32 v15, 0x61, v14
	s_nop 0
	v_cndmask_b32_e32 v80, v185, v80, vcc
	v_cmp_le_i32_e32 vcc, v15, v192
	v_add_u32_e32 v15, 0x42, v14
	s_nop 0
	v_cndmask_b32_e32 v97, v185, v97, vcc
	v_cmp_le_i32_e32 vcc, v15, v192
	v_add_u32_e32 v15, 0x62, v14
	s_nop 0
	v_cndmask_b32_e32 v82, v185, v82, vcc
	v_cmp_le_i32_e32 vcc, v15, v192
	v_add_u32_e32 v15, 0x43, v14
	s_nop 0
	v_cndmask_b32_e32 v98, v185, v98, vcc
	v_cmp_le_i32_e32 vcc, v15, v192
	v_add_u32_e32 v15, 0x63, v14
	s_nop 0
	v_cndmask_b32_e32 v83, v185, v83, vcc
	v_cmp_le_i32_e32 vcc, v15, v192
	v_add_u32_e32 v15, 0x48, v14
	s_nop 0
	v_cndmask_b32_e32 v99, v185, v99, vcc
	v_cmp_le_i32_e32 vcc, v15, v192
	v_add_u32_e32 v15, 0x68, v14
	s_nop 0
	v_cndmask_b32_e32 v84, v185, v84, vcc
	v_cmp_le_i32_e32 vcc, v15, v192
	v_add_u32_e32 v15, 0x49, v14
	s_nop 0
	v_cndmask_b32_e32 v100, v185, v100, vcc
	v_cmp_le_i32_e32 vcc, v15, v192
	v_add_u32_e32 v15, 0x69, v14
	s_nop 0
	v_cndmask_b32_e32 v85, v185, v85, vcc
	v_cmp_le_i32_e32 vcc, v15, v192
	v_add_u32_e32 v15, 0x4a, v14
	s_nop 0
	v_cndmask_b32_e32 v101, v185, v101, vcc
	v_cmp_le_i32_e32 vcc, v15, v192
	v_add_u32_e32 v15, 0x6a, v14
	s_nop 0
	v_cndmask_b32_e32 v86, v185, v86, vcc
	v_cmp_le_i32_e32 vcc, v15, v192
	v_add_u32_e32 v15, 0x4b, v14
	s_nop 0
	v_cndmask_b32_e32 v102, v185, v102, vcc
	v_cmp_le_i32_e32 vcc, v15, v192
	v_add_u32_e32 v15, 0x6b, v14
	s_nop 0
	v_cndmask_b32_e32 v87, v185, v87, vcc
	v_cmp_le_i32_e32 vcc, v15, v192
	v_add_u32_e32 v15, 0x50, v14
	s_nop 0
	v_cndmask_b32_e32 v103, v185, v103, vcc
	v_cmp_le_i32_e32 vcc, v15, v192
	v_add_u32_e32 v15, 0x70, v14
	s_nop 0
	v_cndmask_b32_e32 v88, v185, v88, vcc
	v_cmp_le_i32_e32 vcc, v15, v192
	v_add_u32_e32 v15, 0x51, v14
	s_nop 0
	v_cndmask_b32_e32 v104, v185, v104, vcc
	v_cmp_le_i32_e32 vcc, v15, v192
	v_add_u32_e32 v15, 0x71, v14
	s_nop 0
	v_cndmask_b32_e32 v89, v185, v89, vcc
	v_cmp_le_i32_e32 vcc, v15, v192
	v_add_u32_e32 v15, 0x52, v14
	s_nop 0
	v_cndmask_b32_e32 v105, v185, v105, vcc
	v_cmp_le_i32_e32 vcc, v15, v192
	v_add_u32_e32 v15, 0x72, v14
	s_nop 0
	v_cndmask_b32_e32 v90, v185, v90, vcc
	v_cmp_le_i32_e32 vcc, v15, v192
	v_add_u32_e32 v15, 0x53, v14
	s_nop 0
	v_cndmask_b32_e32 v106, v185, v106, vcc
	v_cmp_le_i32_e32 vcc, v15, v192
	v_add_u32_e32 v15, 0x73, v14
	s_nop 0
	v_cndmask_b32_e32 v91, v185, v91, vcc
	v_cmp_le_i32_e32 vcc, v15, v192
	v_add_u32_e32 v15, 0x58, v14
	s_nop 0
	v_cndmask_b32_e32 v107, v185, v107, vcc
	v_cmp_le_i32_e32 vcc, v15, v192
	v_add_u32_e32 v15, 0x78, v14
	s_nop 0
	v_cndmask_b32_e32 v92, v185, v92, vcc
	v_cmp_le_i32_e32 vcc, v15, v192
	v_add_u32_e32 v15, 0x59, v14
	s_nop 0
	v_cndmask_b32_e32 v108, v185, v108, vcc
	v_cmp_le_i32_e32 vcc, v15, v192
	v_add_u32_e32 v15, 0x79, v14
	s_nop 0
	v_cndmask_b32_e32 v93, v185, v93, vcc
	v_cmp_le_i32_e32 vcc, v15, v192
	v_add_u32_e32 v15, 0x5a, v14
	s_nop 0
	v_cndmask_b32_e32 v109, v185, v109, vcc
	v_cmp_le_i32_e32 vcc, v15, v192
	v_add_u32_e32 v15, 0x7a, v14
	s_nop 0
	v_cndmask_b32_e32 v94, v185, v94, vcc
	v_cmp_le_i32_e32 vcc, v15, v192
	v_add_u32_e32 v15, 0x5b, v14
	v_add_u32_e32 v14, 0x7b, v14
	v_cndmask_b32_e32 v110, v185, v110, vcc
	v_cmp_le_i32_e32 vcc, v15, v192
	s_nop 1
	v_cndmask_b32_e32 v95, v185, v95, vcc
	v_cmp_le_i32_e32 vcc, v14, v192
	s_nop 1
	v_cndmask_b32_e32 v111, v185, v111, vcc

.LBB0_1094:
	s_waitcnt lgkmcnt(0)
	s_barrier
	s_setprio 1
	s_and_b64 vcc, exec, s[4:5]
	s_cbranch_vccnz .LBB0_1096
	ds_read_b128 v[196:199], v0 offset:9216
	ds_read_b128 v[200:203], v0 offset:9248
	s_waitcnt lgkmcnt(1)
	v_mfma_f32_32x32x16_bf16 v[64:79], v[196:199], v[140:143], v[64:79]
	ds_read_b128 v[196:199], v0 offset:13824
	ds_read_b128 v[204:207], v0 offset:13856
	s_waitcnt lgkmcnt(1)
	v_mfma_f32_32x32x16_bf16 v[48:63], v[196:199], v[140:143], v[48:63]
	ds_read_b128 v[196:199], v0 offset:18432
	ds_read_b128 v[208:211], v0 offset:18464
	s_waitcnt lgkmcnt(1)
	v_mfma_f32_32x32x16_bf16 v[32:47], v[196:199], v[140:143], v[32:47]
	ds_read_b128 v[196:199], v0 offset:23040
	ds_read_b128 v[212:215], v0 offset:23072
	v_mfma_f32_32x32x16_bf16 v[64:79], v[200:203], v[144:147], v[64:79]
	s_waitcnt lgkmcnt(1)
	v_mfma_f32_32x32x16_bf16 v[16:31], v[196:199], v[140:143], v[16:31]
	ds_read_b128 v[196:199], v0 offset:9280
	ds_read_b128 v[200:203], v0 offset:9312
	v_mfma_f32_32x32x16_bf16 v[48:63], v[204:207], v[144:147], v[48:63]
	v_mfma_f32_32x32x16_bf16 v[32:47], v[208:211], v[144:147], v[32:47]
	s_waitcnt lgkmcnt(1)
	v_mfma_f32_32x32x16_bf16 v[64:79], v[196:199], v[148:151], v[64:79]
	ds_read_b128 v[196:199], v0 offset:13888
	ds_read_b128 v[204:207], v0 offset:13920
	v_mfma_f32_32x32x16_bf16 v[16:31], v[212:215], v[144:147], v[16:31]
	s_waitcnt lgkmcnt(1)
	v_mfma_f32_32x32x16_bf16 v[48:63], v[196:199], v[148:151], v[48:63]
	ds_read_b128 v[196:199], v0 offset:18496
	ds_read_b128 v[208:211], v0 offset:18528
	s_waitcnt lgkmcnt(1)
	v_mfma_f32_32x32x16_bf16 v[32:47], v[196:199], v[148:151], v[32:47]
	ds_read_b128 v[196:199], v0 offset:23104
	ds_read_b128 v[212:215], v0 offset:23136
	s_waitcnt lgkmcnt(1)
	v_mfma_f32_32x32x16_bf16 v[16:31], v[196:199], v[148:151], v[16:31]
	v_mfma_f32_32x32x16_bf16 v[64:79], v[200:203], v[152:155], v[64:79]
	v_mfma_f32_32x32x16_bf16 v[48:63], v[204:207], v[152:155], v[48:63]
	v_mfma_f32_32x32x16_bf16 v[32:47], v[208:211], v[152:155], v[32:47]
	s_waitcnt lgkmcnt(0)
	v_mfma_f32_32x32x16_bf16 v[16:31], v[212:215], v[152:155], v[16:31]

; template <int DK, int DV>
; __device__ __forceinline__ void attn_unit(LAS unsigned char* lds, const bf16* Qp, int ldq, const bf16* Kp, int ldk, const bf16* VTp, bf16* Op, int ldo, int qb) {
;     ...
;     for (int t = 0; t < NT; t += 2) {
;         ATT_STEP(t, kra, vra, krb, vrb);
;         ATT_STEP(t + 1, krb, vrb, kra, vra);
;     }
.LBB0_1098:
	s_setprio 0
	v_add_u32_e32 v0, s51, v188
	s_waitcnt vmcnt(5)
	ds_write_b128 v0, v[10:13]
	v_add_u32_e32 v0, s51, v186
	v_add_u32_e32 v10, v0, v175
	v_add_u32_e32 v0, v0, v187
	s_waitcnt vmcnt(4)
	ds_write_b128 v10, v[2:5] offset:9216
	s_waitcnt vmcnt(3)
	ds_write_b128 v0, v[6:9] offset:9216
	s_waitcnt lgkmcnt(0)
	s_barrier
	s_addk_i32 s47, 0x80
	s_and_b64 vcc, exec, s[4:5]
	s_cbranch_vccnz .LBB0_1100
	s_mov_b32 s0, s50
	s_mov_b32 s50, s55
	s_branch .LBB0_1072
